# attn_d: LDS fragment prefetch depth 5 (was 4)
# speedup vs baseline: 1.0230x; 1.0230x over previous
.Ld_loopB:
	global_load_dwordx4 v[212:215], v173, s[80:81]
	global_load_dwordx4 v[220:223], v175, s[96:97]
	global_load_dwordx4 v[216:219], v173, s[86:87]
	global_load_dwordx4 v[224:227], v175, s[98:99]
	ds_read_b128 v[228:231], v255 offset:0
	ds_read_b128 v[232:235], v255 offset:64
	ds_read_b128 v[236:239], v255 offset:4608
	ds_read_b128 v[240:243], v255 offset:4672
	ds_read_b128 v[244:247], v255 offset:9216
	v_max3_f32 v26, v88, v89, v90
	v_max3_f32 v26, v26, v91, v92
	v_max3_f32 v26, v26, v93, v94
	v_max3_f32 v26, v26, v95, v96
	v_max3_f32 v26, v26, v97, v98
	v_max3_f32 v26, v26, v99, v100
	v_max3_f32 v26, v26, v101, v102
	v_max_f32_e32 v26, v26, v103
	v_cmp_lt_f32_e32 vcc, s66, v26
	s_cbranch_vccz .Ld_nr_B0_0
	v_mov_b32_e32 v27, v26
	s_nop 1
	v_permlane16_swap_b32_e32 v26, v27
	v_max_f32_e32 v26, v26, v27
	v_mov_b32_e32 v27, v26
	s_nop 1
	v_permlane32_swap_b32_e32 v26, v27
	v_max_f32_e32 v26, v26, v27
	v_cmp_lt_f32_e32 vcc, s66, v26
	s_nop 1
	v_cndmask_b32_e32 v3, 0, v26, vcc
	v_sub_f32_e32 v2, 0, v3
	v_min_f32_e32 v2, 0, v2
	v_exp_f32_e32 v2, v2
	v_sub_f32_e32 v24, v24, v3
	v_mul_f32_e32 v0, v0, v2
	v_mul_f32_e32 v28, v28, v2
	v_mul_f32_e32 v29, v29, v2
	v_mul_f32_e32 v30, v30, v2
	v_mul_f32_e32 v31, v31, v2
	v_mul_f32_e32 v32, v32, v2
	v_mul_f32_e32 v33, v33, v2
	v_mul_f32_e32 v34, v34, v2
	v_mul_f32_e32 v35, v35, v2
	v_mul_f32_e32 v40, v40, v2
	v_mul_f32_e32 v41, v41, v2
	v_mul_f32_e32 v42, v42, v2
	v_mul_f32_e32 v43, v43, v2
	v_mul_f32_e32 v52, v52, v2
	v_mul_f32_e32 v53, v53, v2
	v_mul_f32_e32 v54, v54, v2
	v_mul_f32_e32 v55, v55, v2
	v_mul_f32_e32 v56, v56, v2
	v_mul_f32_e32 v57, v57, v2
	v_mul_f32_e32 v58, v58, v2
	v_mul_f32_e32 v59, v59, v2
	v_mul_f32_e32 v64, v64, v2
	v_mul_f32_e32 v65, v65, v2
	v_mul_f32_e32 v66, v66, v2
	v_mul_f32_e32 v67, v67, v2
	v_mul_f32_e32 v72, v72, v2
	v_mul_f32_e32 v73, v73, v2
	v_mul_f32_e32 v74, v74, v2
	v_mul_f32_e32 v75, v75, v2
	v_mul_f32_e32 v84, v84, v2
	v_mul_f32_e32 v85, v85, v2
	v_mul_f32_e32 v86, v86, v2
	v_mul_f32_e32 v87, v87, v2
	v_sub_f32_e32 v88, v88, v3
	v_sub_f32_e32 v89, v89, v3
	v_sub_f32_e32 v90, v90, v3
	v_sub_f32_e32 v91, v91, v3
	v_sub_f32_e32 v92, v92, v3
	v_sub_f32_e32 v93, v93, v3
	v_sub_f32_e32 v94, v94, v3
	v_sub_f32_e32 v95, v95, v3
	v_sub_f32_e32 v96, v96, v3
	v_sub_f32_e32 v97, v97, v3
	v_sub_f32_e32 v98, v98, v3
	v_sub_f32_e32 v99, v99, v3
	v_sub_f32_e32 v100, v100, v3
	v_sub_f32_e32 v101, v101, v3
	v_sub_f32_e32 v102, v102, v3
	v_sub_f32_e32 v103, v103, v3

.Ld_nr_B0_1:
	v_exp_f32_e32 v104, v104
	v_exp_f32_e32 v105, v105
	v_exp_f32_e32 v106, v106
	v_exp_f32_e32 v107, v107
	v_exp_f32_e32 v108, v108
	v_exp_f32_e32 v109, v109
	v_exp_f32_e32 v110, v110
	v_exp_f32_e32 v111, v111
	v_exp_f32_e32 v112, v112
	v_exp_f32_e32 v113, v113
	v_exp_f32_e32 v114, v114
	v_exp_f32_e32 v115, v115
	v_exp_f32_e32 v116, v116
	v_exp_f32_e32 v117, v117
	v_exp_f32_e32 v118, v118
	v_exp_f32_e32 v119, v119
	s_nop 0
	v_add_f32_e32 v26, v104, v105
	v_add_f32_e32 v26, v26, v106
	v_add_f32_e32 v26, v26, v107
	v_add_f32_e32 v26, v26, v108
	v_add_f32_e32 v26, v26, v109
	v_add_f32_e32 v26, v26, v110
	v_add_f32_e32 v26, v26, v111
	v_add_f32_e32 v26, v26, v112
	v_add_f32_e32 v26, v26, v113
	v_add_f32_e32 v26, v26, v114
	v_add_f32_e32 v26, v26, v115
	v_add_f32_e32 v26, v26, v116
	v_add_f32_e32 v26, v26, v117
	v_add_f32_e32 v26, v26, v118
	v_add_f32_e32 v26, v26, v119
	v_add_f32_e32 v151, v151, v26
	v_cvt_pk_bf16_f32 v128, v104, v105
	v_cvt_pk_bf16_f32 v129, v106, v107
	v_cvt_pk_bf16_f32 v130, v108, v109
	v_cvt_pk_bf16_f32 v131, v110, v111
	v_cvt_pk_bf16_f32 v152, v112, v113
	v_cvt_pk_bf16_f32 v153, v114, v115
	v_cvt_pk_bf16_f32 v154, v116, v117
	v_cvt_pk_bf16_f32 v155, v118, v119
	v_mov_b32_e32 v156, v165
	v_add_f32_e32 v157, 0x3f800000, v165
	v_add_f32_e32 v158, 0x40000000, v165
	v_add_f32_e32 v159, 0x40400000, v165
	v_add_f32_e32 v160, 0x41800000, v165
	v_add_f32_e32 v161, 0x41880000, v165
	v_add_f32_e32 v162, 0x41900000, v165
	v_add_f32_e32 v163, 0x41980000, v165
	v_add_f32_e32 v176, 0x42000000, v165
	v_add_f32_e32 v177, 0x42040000, v165
	v_add_f32_e32 v178, 0x42080000, v165
	v_add_f32_e32 v179, 0x420c0000, v165
	v_add_f32_e32 v180, 0x42400000, v165
	v_add_f32_e32 v181, 0x42440000, v165
	v_add_f32_e32 v182, 0x42480000, v165
	v_add_f32_e32 v183, 0x424c0000, v165
	v_fma_f32 v204, -v150, |v156|, v25
	v_fma_f32 v205, -v150, |v157|, v25
	v_fma_f32 v206, -v150, |v158|, v25
	v_fma_f32 v207, -v150, |v159|, v25
	v_fma_f32 v208, -v150, |v160|, v25
	v_fma_f32 v209, -v150, |v161|, v25
	v_fma_f32 v210, -v150, |v162|, v25
	v_fma_f32 v211, -v150, |v163|, v25
	v_fma_f32 v184, -v150, |v176|, v25
	v_fma_f32 v185, -v150, |v177|, v25
	v_fma_f32 v186, -v150, |v178|, v25
	v_fma_f32 v187, -v150, |v179|, v25
	v_fma_f32 v188, -v150, |v180|, v25
	v_fma_f32 v189, -v150, |v181|, v25
	v_fma_f32 v190, -v150, |v182|, v25
	v_fma_f32 v191, -v150, |v183|, v25
	v_fma_f32 v156, -v150, |v156|, v24
	v_fma_f32 v157, -v150, |v157|, v24
	v_fma_f32 v158, -v150, |v158|, v24
	v_fma_f32 v159, -v150, |v159|, v24
	v_fma_f32 v160, -v150, |v160|, v24
	v_fma_f32 v161, -v150, |v161|, v24
	v_fma_f32 v162, -v150, |v162|, v24
	v_fma_f32 v163, -v150, |v163|, v24
	v_fma_f32 v176, -v150, |v176|, v24
	v_fma_f32 v177, -v150, |v177|, v24
	v_fma_f32 v178, -v150, |v178|, v24
	v_fma_f32 v179, -v150, |v179|, v24
	v_fma_f32 v180, -v150, |v180|, v24
	v_fma_f32 v181, -v150, |v181|, v24
	v_fma_f32 v182, -v150, |v182|, v24
	v_fma_f32 v183, -v150, |v183|, v24
	ds_read_b128 v[248:251], v255 offset:9280
	s_waitcnt lgkmcnt(5)
	v_mfma_f32_16x16x32_bf16 v[88:91], v[228:231], v[4:7], v[156:159]
	ds_read_b128 v[228:231], v255 offset:13824
	s_waitcnt lgkmcnt(5)
	v_mfma_f32_16x16x32_bf16 v[88:91], v[232:235], v[8:11], v[88:91]
	ds_read_b128 v[232:235], v255 offset:13888
	s_waitcnt lgkmcnt(5)
	v_mfma_f32_16x16x32_bf16 v[92:95], v[236:239], v[4:7], v[160:163]
	ds_read_b128 v[236:239], v255 offset:128
	s_waitcnt lgkmcnt(5)
	v_mfma_f32_16x16x32_bf16 v[92:95], v[240:243], v[8:11], v[92:95]
	ds_read_b128 v[240:243], v255 offset:192
	s_waitcnt lgkmcnt(5)
	v_mfma_f32_16x16x32_bf16 v[96:99], v[244:247], v[4:7], v[176:179]
	ds_read_b128 v[244:247], v255 offset:4736
	s_waitcnt lgkmcnt(5)
	v_mfma_f32_16x16x32_bf16 v[96:99], v[248:251], v[8:11], v[96:99]
	ds_read_b128 v[248:251], v255 offset:4800
	s_waitcnt lgkmcnt(5)
	v_mfma_f32_16x16x32_bf16 v[100:103], v[228:231], v[4:7], v[180:183]
	ds_read_b128 v[228:231], v255 offset:9344
	s_waitcnt lgkmcnt(5)
	v_mfma_f32_16x16x32_bf16 v[100:103], v[232:235], v[8:11], v[100:103]
	ds_read_b128 v[232:235], v255 offset:9408
	s_waitcnt lgkmcnt(5)
	v_mfma_f32_16x16x32_bf16 v[104:107], v[236:239], v[12:15], v[204:207]
	ds_read_b128 v[236:239], v255 offset:13952
	s_waitcnt lgkmcnt(5)
	v_mfma_f32_16x16x32_bf16 v[104:107], v[240:243], v[16:19], v[104:107]
	ds_read_b128 v[240:243], v255 offset:14016
	s_waitcnt lgkmcnt(5)
	v_mfma_f32_16x16x32_bf16 v[108:111], v[244:247], v[12:15], v[208:211]
	ds_read_b64_tr_b16 v[244:245], v174 offset:36864
	ds_read_b64_tr_b16 v[246:247], v174 offset:41472
	s_waitcnt lgkmcnt(6)
	v_mfma_f32_16x16x32_bf16 v[108:111], v[248:251], v[16:19], v[108:111]
	ds_read_b64_tr_b16 v[248:249], v174 offset:36896
	ds_read_b64_tr_b16 v[250:251], v174 offset:41504
	s_waitcnt lgkmcnt(7)
	v_mfma_f32_16x16x32_bf16 v[112:115], v[228:231], v[12:15], v[184:187]
	ds_read_b64_tr_b16 v[228:229], v174 offset:36928
	ds_read_b64_tr_b16 v[230:231], v174 offset:41536
	s_waitcnt lgkmcnt(8)
	v_mfma_f32_16x16x32_bf16 v[112:115], v[232:235], v[16:19], v[112:115]
	ds_read_b64_tr_b16 v[232:233], v174 offset:36960
	ds_read_b64_tr_b16 v[234:235], v174 offset:41568
	s_waitcnt lgkmcnt(9)
	v_mfma_f32_16x16x32_bf16 v[116:119], v[236:239], v[12:15], v[188:191]
	ds_read_b64_tr_b16 v[236:237], v174 offset:36992
	ds_read_b64_tr_b16 v[238:239], v174 offset:41600
	s_waitcnt lgkmcnt(10)
	v_mfma_f32_16x16x32_bf16 v[116:119], v[240:243], v[16:19], v[116:119]
	ds_read_b64_tr_b16 v[240:241], v174 offset:37024
	ds_read_b64_tr_b16 v[242:243], v174 offset:41632
	s_waitcnt lgkmcnt(10)
	v_mfma_f32_16x16x32_bf16 v[28:31], v[244:247], v[120:123], v[28:31]
	v_mfma_f32_16x16x32_bf16 v[36:39], v[244:247], v[128:131], v[36:39]
	ds_read_b64_tr_b16 v[244:245], v174 offset:37056
	ds_read_b64_tr_b16 v[246:247], v174 offset:41664
	s_waitcnt lgkmcnt(10)
	v_mfma_f32_16x16x32_bf16 v[32:35], v[248:251], v[120:123], v[32:35]
	v_mfma_f32_16x16x32_bf16 v[44:47], v[248:251], v[128:131], v[44:47]
	ds_read_b64_tr_b16 v[248:249], v174 offset:37088
	ds_read_b64_tr_b16 v[250:251], v174 offset:41696
	s_waitcnt lgkmcnt(10)
	v_mfma_f32_16x16x32_bf16 v[40:43], v[228:231], v[120:123], v[40:43]
	v_mfma_f32_16x16x32_bf16 v[48:51], v[228:231], v[128:131], v[48:51]
	ds_read_b64_tr_b16 v[228:229], v174 offset:46080
	ds_read_b64_tr_b16 v[230:231], v174 offset:50688
	s_waitcnt lgkmcnt(10)
	v_mfma_f32_16x16x32_bf16 v[52:55], v[232:235], v[120:123], v[52:55]
	v_mfma_f32_16x16x32_bf16 v[60:63], v[232:235], v[128:131], v[60:63]
	ds_read_b64_tr_b16 v[232:233], v174 offset:46112
	ds_read_b64_tr_b16 v[234:235], v174 offset:50720
	s_waitcnt lgkmcnt(10)
	v_mfma_f32_16x16x32_bf16 v[56:59], v[236:239], v[120:123], v[56:59]
	v_mfma_f32_16x16x32_bf16 v[68:71], v[236:239], v[128:131], v[68:71]
	ds_read_b64_tr_b16 v[236:237], v174 offset:46144
	ds_read_b64_tr_b16 v[238:239], v174 offset:50752
	s_waitcnt lgkmcnt(10)
	v_mfma_f32_16x16x32_bf16 v[64:67], v[240:243], v[120:123], v[64:67]
	v_mfma_f32_16x16x32_bf16 v[76:79], v[240:243], v[128:131], v[76:79]
	ds_read_b64_tr_b16 v[240:241], v174 offset:46176
	ds_read_b64_tr_b16 v[242:243], v174 offset:50784
	s_waitcnt lgkmcnt(10)
	v_mfma_f32_16x16x32_bf16 v[72:75], v[244:247], v[120:123], v[72:75]
	v_mfma_f32_16x16x32_bf16 v[80:83], v[244:247], v[128:131], v[80:83]
	ds_read_b64_tr_b16 v[244:245], v174 offset:46208
	ds_read_b64_tr_b16 v[246:247], v174 offset:50816
	s_waitcnt lgkmcnt(10)
	v_mfma_f32_16x16x32_bf16 v[84:87], v[248:251], v[120:123], v[84:87]
	v_mfma_f32_16x16x32_bf16 v[20:23], v[248:251], v[128:131], v[20:23]
	ds_read_b64_tr_b16 v[248:249], v174 offset:46240
	ds_read_b64_tr_b16 v[250:251], v174 offset:50848
	s_waitcnt lgkmcnt(10)
	v_mfma_f32_16x16x32_bf16 v[28:31], v[228:231], v[124:127], v[28:31]
	v_mfma_f32_16x16x32_bf16 v[36:39], v[228:231], v[152:155], v[36:39]
	ds_read_b64_tr_b16 v[228:229], v174 offset:46272
	ds_read_b64_tr_b16 v[230:231], v174 offset:50880
	s_waitcnt lgkmcnt(10)
	v_mfma_f32_16x16x32_bf16 v[32:35], v[232:235], v[124:127], v[32:35]
	v_mfma_f32_16x16x32_bf16 v[44:47], v[232:235], v[152:155], v[44:47]
	ds_read_b64_tr_b16 v[232:233], v174 offset:46304
	ds_read_b64_tr_b16 v[234:235], v174 offset:50912
	s_waitcnt lgkmcnt(10)
	v_mfma_f32_16x16x32_bf16 v[40:43], v[236:239], v[124:127], v[40:43]
	v_mfma_f32_16x16x32_bf16 v[48:51], v[236:239], v[152:155], v[48:51]
	s_waitcnt lgkmcnt(8)
	v_mfma_f32_16x16x32_bf16 v[52:55], v[240:243], v[124:127], v[52:55]
	v_mfma_f32_16x16x32_bf16 v[60:63], v[240:243], v[152:155], v[60:63]
	s_waitcnt lgkmcnt(6)
	v_mfma_f32_16x16x32_bf16 v[56:59], v[244:247], v[124:127], v[56:59]
	v_mfma_f32_16x16x32_bf16 v[68:71], v[244:247], v[152:155], v[68:71]
	s_waitcnt lgkmcnt(4)
	v_mfma_f32_16x16x32_bf16 v[64:67], v[248:251], v[124:127], v[64:67]
	v_mfma_f32_16x16x32_bf16 v[76:79], v[248:251], v[152:155], v[76:79]
	s_waitcnt lgkmcnt(2)
	v_mfma_f32_16x16x32_bf16 v[72:75], v[228:231], v[124:127], v[72:75]
	v_mfma_f32_16x16x32_bf16 v[80:83], v[228:231], v[152:155], v[80:83]
	s_waitcnt lgkmcnt(0)
	v_mfma_f32_16x16x32_bf16 v[84:87], v[232:235], v[124:127], v[84:87]
	v_mfma_f32_16x16x32_bf16 v[20:23], v[232:235], v[152:155], v[20:23]
	s_waitcnt vmcnt(4)
	ds_write_b128 v169, v[138:141] offset:18432
	ds_write_b128 v169, v[142:145] offset:27648
	ds_write_b128 v164, v[146:149] offset:36864
	ds_write_b128 v164, v[194:197] offset:46080
	s_mov_b32 s31, s38
	s_mov_b32 s38, s39
	s_add_i32 s39, s39, 0x4800
	s_cmp_lg_u32 s39, 0xd800
	s_cselect_b32 s39, s39, 0
	s_mov_b32 s66, 0xff800000
	s_cmp_ge_u32 s5, 1
	s_cselect_b32 s66, 0x42800000, s66
	s_add_i32 s5, s5, 1
	s_add_i32 s8, s5, 2
	s_min_u32 s8, s8, 63
	s_mul_i32 s30, s8, 0xf8000
	v_add_f32_e32 v165, 0x42800000, v165
	v_add_u32_e32 v174, s31, v168
	v_add_u32_e32 v164, s39, v169
	s_add_u32 s80, s42, s30
	s_addc_u32 s81, s43, 0
	s_add_u32 s86, s80, 0x7c000
	s_addc_u32 s87, s81, 0
	s_add_u32 s96, s46, s30
	s_addc_u32 s97, s47, 0
	s_add_u32 s98, s96, 0x7c000
	s_addc_u32 s99, s97, 0
	s_waitcnt lgkmcnt(0)
	s_barrier
	global_load_dwordx4 v[138:141], v173, s[80:81]
	global_load_dwordx4 v[146:149], v175, s[96:97]
	global_load_dwordx4 v[142:145], v173, s[86:87]
	global_load_dwordx4 v[194:197], v175, s[98:99]
	ds_read_b128 v[228:231], v255 offset:18432
	ds_read_b128 v[232:235], v255 offset:18496
	ds_read_b128 v[236:239], v255 offset:23040
	ds_read_b128 v[240:243], v255 offset:23104
	ds_read_b128 v[244:247], v255 offset:27648
	v_max3_f32 v26, v88, v89, v90
	v_max3_f32 v26, v26, v91, v92
	v_max3_f32 v26, v26, v93, v94
	v_max3_f32 v26, v26, v95, v96
	v_max3_f32 v26, v26, v97, v98
	v_max3_f32 v26, v26, v99, v100
	v_max3_f32 v26, v26, v101, v102
	v_max_f32_e32 v26, v26, v103
	v_cmp_lt_f32_e32 vcc, s66, v26
	s_cbranch_vccz .Ld_nr_B1_0
	v_mov_b32_e32 v27, v26
	s_nop 1
	v_permlane16_swap_b32_e32 v26, v27
	v_max_f32_e32 v26, v26, v27
	v_mov_b32_e32 v27, v26
	s_nop 1
	v_permlane32_swap_b32_e32 v26, v27
	v_max_f32_e32 v26, v26, v27
	v_cmp_lt_f32_e32 vcc, s66, v26
	s_nop 1
	v_cndmask_b32_e32 v3, 0, v26, vcc
	v_sub_f32_e32 v2, 0, v3
	v_min_f32_e32 v2, 0, v2
	v_exp_f32_e32 v2, v2
	v_sub_f32_e32 v24, v24, v3
	v_mul_f32_e32 v0, v0, v2
	v_mul_f32_e32 v28, v28, v2
	v_mul_f32_e32 v29, v29, v2
	v_mul_f32_e32 v30, v30, v2
	v_mul_f32_e32 v31, v31, v2
	v_mul_f32_e32 v32, v32, v2
	v_mul_f32_e32 v33, v33, v2
	v_mul_f32_e32 v34, v34, v2
	v_mul_f32_e32 v35, v35, v2
	v_mul_f32_e32 v40, v40, v2
	v_mul_f32_e32 v41, v41, v2
	v_mul_f32_e32 v42, v42, v2
	v_mul_f32_e32 v43, v43, v2
	v_mul_f32_e32 v52, v52, v2
	v_mul_f32_e32 v53, v53, v2
	v_mul_f32_e32 v54, v54, v2
	v_mul_f32_e32 v55, v55, v2
	v_mul_f32_e32 v56, v56, v2
	v_mul_f32_e32 v57, v57, v2
	v_mul_f32_e32 v58, v58, v2
	v_mul_f32_e32 v59, v59, v2
	v_mul_f32_e32 v64, v64, v2
	v_mul_f32_e32 v65, v65, v2
	v_mul_f32_e32 v66, v66, v2
	v_mul_f32_e32 v67, v67, v2
	v_mul_f32_e32 v72, v72, v2
	v_mul_f32_e32 v73, v73, v2
	v_mul_f32_e32 v74, v74, v2
	v_mul_f32_e32 v75, v75, v2
	v_mul_f32_e32 v84, v84, v2
	v_mul_f32_e32 v85, v85, v2
	v_mul_f32_e32 v86, v86, v2
	v_mul_f32_e32 v87, v87, v2
	v_sub_f32_e32 v88, v88, v3
	v_sub_f32_e32 v89, v89, v3
	v_sub_f32_e32 v90, v90, v3
	v_sub_f32_e32 v91, v91, v3
	v_sub_f32_e32 v92, v92, v3
	v_sub_f32_e32 v93, v93, v3
	v_sub_f32_e32 v94, v94, v3
	v_sub_f32_e32 v95, v95, v3
	v_sub_f32_e32 v96, v96, v3
	v_sub_f32_e32 v97, v97, v3
	v_sub_f32_e32 v98, v98, v3
	v_sub_f32_e32 v99, v99, v3
	v_sub_f32_e32 v100, v100, v3
	v_sub_f32_e32 v101, v101, v3
	v_sub_f32_e32 v102, v102, v3
	v_sub_f32_e32 v103, v103, v3

.Ld_nr_B1_1:
	v_exp_f32_e32 v104, v104
	v_exp_f32_e32 v105, v105
	v_exp_f32_e32 v106, v106
	v_exp_f32_e32 v107, v107
	v_exp_f32_e32 v108, v108
	v_exp_f32_e32 v109, v109
	v_exp_f32_e32 v110, v110
	v_exp_f32_e32 v111, v111
	v_exp_f32_e32 v112, v112
	v_exp_f32_e32 v113, v113
	v_exp_f32_e32 v114, v114
	v_exp_f32_e32 v115, v115
	v_exp_f32_e32 v116, v116
	v_exp_f32_e32 v117, v117
	v_exp_f32_e32 v118, v118
	v_exp_f32_e32 v119, v119
	s_nop 0
	v_add_f32_e32 v26, v104, v105
	v_add_f32_e32 v26, v26, v106
	v_add_f32_e32 v26, v26, v107
	v_add_f32_e32 v26, v26, v108
	v_add_f32_e32 v26, v26, v109
	v_add_f32_e32 v26, v26, v110
	v_add_f32_e32 v26, v26, v111
	v_add_f32_e32 v26, v26, v112
	v_add_f32_e32 v26, v26, v113
	v_add_f32_e32 v26, v26, v114
	v_add_f32_e32 v26, v26, v115
	v_add_f32_e32 v26, v26, v116
	v_add_f32_e32 v26, v26, v117
	v_add_f32_e32 v26, v26, v118
	v_add_f32_e32 v26, v26, v119
	v_add_f32_e32 v151, v151, v26
	v_cvt_pk_bf16_f32 v128, v104, v105
	v_cvt_pk_bf16_f32 v129, v106, v107
	v_cvt_pk_bf16_f32 v130, v108, v109
	v_cvt_pk_bf16_f32 v131, v110, v111
	v_cvt_pk_bf16_f32 v152, v112, v113
	v_cvt_pk_bf16_f32 v153, v114, v115
	v_cvt_pk_bf16_f32 v154, v116, v117
	v_cvt_pk_bf16_f32 v155, v118, v119
	v_mov_b32_e32 v156, v165
	v_add_f32_e32 v157, 0x3f800000, v165
	v_add_f32_e32 v158, 0x40000000, v165
	v_add_f32_e32 v159, 0x40400000, v165
	v_add_f32_e32 v160, 0x41800000, v165
	v_add_f32_e32 v161, 0x41880000, v165
	v_add_f32_e32 v162, 0x41900000, v165
	v_add_f32_e32 v163, 0x41980000, v165
	v_add_f32_e32 v176, 0x42000000, v165
	v_add_f32_e32 v177, 0x42040000, v165
	v_add_f32_e32 v178, 0x42080000, v165
	v_add_f32_e32 v179, 0x420c0000, v165
	v_add_f32_e32 v180, 0x42400000, v165
	v_add_f32_e32 v181, 0x42440000, v165
	v_add_f32_e32 v182, 0x42480000, v165
	v_add_f32_e32 v183, 0x424c0000, v165
	v_fma_f32 v204, -v150, |v156|, v25
	v_fma_f32 v205, -v150, |v157|, v25
	v_fma_f32 v206, -v150, |v158|, v25
	v_fma_f32 v207, -v150, |v159|, v25
	v_fma_f32 v208, -v150, |v160|, v25
	v_fma_f32 v209, -v150, |v161|, v25
	v_fma_f32 v210, -v150, |v162|, v25
	v_fma_f32 v211, -v150, |v163|, v25
	v_fma_f32 v184, -v150, |v176|, v25
	v_fma_f32 v185, -v150, |v177|, v25
	v_fma_f32 v186, -v150, |v178|, v25
	v_fma_f32 v187, -v150, |v179|, v25
	v_fma_f32 v188, -v150, |v180|, v25
	v_fma_f32 v189, -v150, |v181|, v25
	v_fma_f32 v190, -v150, |v182|, v25
	v_fma_f32 v191, -v150, |v183|, v25
	v_fma_f32 v156, -v150, |v156|, v24
	v_fma_f32 v157, -v150, |v157|, v24
	v_fma_f32 v158, -v150, |v158|, v24
	v_fma_f32 v159, -v150, |v159|, v24
	v_fma_f32 v160, -v150, |v160|, v24
	v_fma_f32 v161, -v150, |v161|, v24
	v_fma_f32 v162, -v150, |v162|, v24
	v_fma_f32 v163, -v150, |v163|, v24
	v_fma_f32 v176, -v150, |v176|, v24
	v_fma_f32 v177, -v150, |v177|, v24
	v_fma_f32 v178, -v150, |v178|, v24
	v_fma_f32 v179, -v150, |v179|, v24
	v_fma_f32 v180, -v150, |v180|, v24
	v_fma_f32 v181, -v150, |v181|, v24
	v_fma_f32 v182, -v150, |v182|, v24
	v_fma_f32 v183, -v150, |v183|, v24
	ds_read_b128 v[248:251], v255 offset:27712
	s_waitcnt lgkmcnt(5)
	v_mfma_f32_16x16x32_bf16 v[88:91], v[228:231], v[4:7], v[156:159]
	ds_read_b128 v[228:231], v255 offset:32256
	s_waitcnt lgkmcnt(5)
	v_mfma_f32_16x16x32_bf16 v[88:91], v[232:235], v[8:11], v[88:91]
	ds_read_b128 v[232:235], v255 offset:32320
	s_waitcnt lgkmcnt(5)
	v_mfma_f32_16x16x32_bf16 v[92:95], v[236:239], v[4:7], v[160:163]
	ds_read_b128 v[236:239], v255 offset:18560
	s_waitcnt lgkmcnt(5)
	v_mfma_f32_16x16x32_bf16 v[92:95], v[240:243], v[8:11], v[92:95]
	ds_read_b128 v[240:243], v255 offset:18624
	s_waitcnt lgkmcnt(5)
	v_mfma_f32_16x16x32_bf16 v[96:99], v[244:247], v[4:7], v[176:179]
	ds_read_b128 v[244:247], v255 offset:23168
	s_waitcnt lgkmcnt(5)
	v_mfma_f32_16x16x32_bf16 v[96:99], v[248:251], v[8:11], v[96:99]
	ds_read_b128 v[248:251], v255 offset:23232
	s_waitcnt lgkmcnt(5)
	v_mfma_f32_16x16x32_bf16 v[100:103], v[228:231], v[4:7], v[180:183]
	ds_read_b128 v[228:231], v255 offset:27776
	s_waitcnt lgkmcnt(5)
	v_mfma_f32_16x16x32_bf16 v[100:103], v[232:235], v[8:11], v[100:103]
	ds_read_b128 v[232:235], v255 offset:27840
	s_waitcnt lgkmcnt(5)
	v_mfma_f32_16x16x32_bf16 v[104:107], v[236:239], v[12:15], v[204:207]
	ds_read_b128 v[236:239], v255 offset:32384
	s_waitcnt lgkmcnt(5)
	v_mfma_f32_16x16x32_bf16 v[104:107], v[240:243], v[16:19], v[104:107]
	ds_read_b128 v[240:243], v255 offset:32448
	s_waitcnt lgkmcnt(5)
	v_mfma_f32_16x16x32_bf16 v[108:111], v[244:247], v[12:15], v[208:211]
	ds_read_b64_tr_b16 v[244:245], v174 offset:36864
	ds_read_b64_tr_b16 v[246:247], v174 offset:41472
	s_waitcnt lgkmcnt(6)
	v_mfma_f32_16x16x32_bf16 v[108:111], v[248:251], v[16:19], v[108:111]
	ds_read_b64_tr_b16 v[248:249], v174 offset:36896
	ds_read_b64_tr_b16 v[250:251], v174 offset:41504
	s_waitcnt lgkmcnt(7)
	v_mfma_f32_16x16x32_bf16 v[112:115], v[228:231], v[12:15], v[184:187]
	ds_read_b64_tr_b16 v[228:229], v174 offset:36928
	ds_read_b64_tr_b16 v[230:231], v174 offset:41536
	s_waitcnt lgkmcnt(8)
	v_mfma_f32_16x16x32_bf16 v[112:115], v[232:235], v[16:19], v[112:115]
	ds_read_b64_tr_b16 v[232:233], v174 offset:36960
	ds_read_b64_tr_b16 v[234:235], v174 offset:41568
	s_waitcnt lgkmcnt(9)
	v_mfma_f32_16x16x32_bf16 v[116:119], v[236:239], v[12:15], v[188:191]
	ds_read_b64_tr_b16 v[236:237], v174 offset:36992
	ds_read_b64_tr_b16 v[238:239], v174 offset:41600
	s_waitcnt lgkmcnt(10)
	v_mfma_f32_16x16x32_bf16 v[116:119], v[240:243], v[16:19], v[116:119]
	ds_read_b64_tr_b16 v[240:241], v174 offset:37024
	ds_read_b64_tr_b16 v[242:243], v174 offset:41632
	s_waitcnt lgkmcnt(10)
	v_mfma_f32_16x16x32_bf16 v[28:31], v[244:247], v[120:123], v[28:31]
	v_mfma_f32_16x16x32_bf16 v[36:39], v[244:247], v[128:131], v[36:39]
	ds_read_b64_tr_b16 v[244:245], v174 offset:37056
	ds_read_b64_tr_b16 v[246:247], v174 offset:41664
	s_waitcnt lgkmcnt(10)
	v_mfma_f32_16x16x32_bf16 v[32:35], v[248:251], v[120:123], v[32:35]
	v_mfma_f32_16x16x32_bf16 v[44:47], v[248:251], v[128:131], v[44:47]
	ds_read_b64_tr_b16 v[248:249], v174 offset:37088
	ds_read_b64_tr_b16 v[250:251], v174 offset:41696
	s_waitcnt lgkmcnt(10)
	v_mfma_f32_16x16x32_bf16 v[40:43], v[228:231], v[120:123], v[40:43]
	v_mfma_f32_16x16x32_bf16 v[48:51], v[228:231], v[128:131], v[48:51]
	ds_read_b64_tr_b16 v[228:229], v174 offset:46080
	ds_read_b64_tr_b16 v[230:231], v174 offset:50688
	s_waitcnt lgkmcnt(10)
	v_mfma_f32_16x16x32_bf16 v[52:55], v[232:235], v[120:123], v[52:55]
	v_mfma_f32_16x16x32_bf16 v[60:63], v[232:235], v[128:131], v[60:63]
	ds_read_b64_tr_b16 v[232:233], v174 offset:46112
	ds_read_b64_tr_b16 v[234:235], v174 offset:50720
	s_waitcnt lgkmcnt(10)
	v_mfma_f32_16x16x32_bf16 v[56:59], v[236:239], v[120:123], v[56:59]
	v_mfma_f32_16x16x32_bf16 v[68:71], v[236:239], v[128:131], v[68:71]
	ds_read_b64_tr_b16 v[236:237], v174 offset:46144
	ds_read_b64_tr_b16 v[238:239], v174 offset:50752
	s_waitcnt lgkmcnt(10)
	v_mfma_f32_16x16x32_bf16 v[64:67], v[240:243], v[120:123], v[64:67]
	v_mfma_f32_16x16x32_bf16 v[76:79], v[240:243], v[128:131], v[76:79]
	ds_read_b64_tr_b16 v[240:241], v174 offset:46176
	ds_read_b64_tr_b16 v[242:243], v174 offset:50784
	s_waitcnt lgkmcnt(10)
	v_mfma_f32_16x16x32_bf16 v[72:75], v[244:247], v[120:123], v[72:75]
	v_mfma_f32_16x16x32_bf16 v[80:83], v[244:247], v[128:131], v[80:83]
	ds_read_b64_tr_b16 v[244:245], v174 offset:46208
	ds_read_b64_tr_b16 v[246:247], v174 offset:50816
	s_waitcnt lgkmcnt(10)
	v_mfma_f32_16x16x32_bf16 v[84:87], v[248:251], v[120:123], v[84:87]
	v_mfma_f32_16x16x32_bf16 v[20:23], v[248:251], v[128:131], v[20:23]
	ds_read_b64_tr_b16 v[248:249], v174 offset:46240
	ds_read_b64_tr_b16 v[250:251], v174 offset:50848
	s_waitcnt lgkmcnt(10)
	v_mfma_f32_16x16x32_bf16 v[28:31], v[228:231], v[124:127], v[28:31]
	v_mfma_f32_16x16x32_bf16 v[36:39], v[228:231], v[152:155], v[36:39]
	ds_read_b64_tr_b16 v[228:229], v174 offset:46272
	ds_read_b64_tr_b16 v[230:231], v174 offset:50880
	s_waitcnt lgkmcnt(10)
	v_mfma_f32_16x16x32_bf16 v[32:35], v[232:235], v[124:127], v[32:35]
	v_mfma_f32_16x16x32_bf16 v[44:47], v[232:235], v[152:155], v[44:47]
	ds_read_b64_tr_b16 v[232:233], v174 offset:46304
	ds_read_b64_tr_b16 v[234:235], v174 offset:50912
	s_waitcnt lgkmcnt(10)
	v_mfma_f32_16x16x32_bf16 v[40:43], v[236:239], v[124:127], v[40:43]
	v_mfma_f32_16x16x32_bf16 v[48:51], v[236:239], v[152:155], v[48:51]
	s_waitcnt lgkmcnt(8)
	v_mfma_f32_16x16x32_bf16 v[52:55], v[240:243], v[124:127], v[52:55]
	v_mfma_f32_16x16x32_bf16 v[60:63], v[240:243], v[152:155], v[60:63]
	s_waitcnt lgkmcnt(6)
	v_mfma_f32_16x16x32_bf16 v[56:59], v[244:247], v[124:127], v[56:59]
	v_mfma_f32_16x16x32_bf16 v[68:71], v[244:247], v[152:155], v[68:71]
	s_waitcnt lgkmcnt(4)
	v_mfma_f32_16x16x32_bf16 v[64:67], v[248:251], v[124:127], v[64:67]
	v_mfma_f32_16x16x32_bf16 v[76:79], v[248:251], v[152:155], v[76:79]
	s_waitcnt lgkmcnt(2)
	v_mfma_f32_16x16x32_bf16 v[72:75], v[228:231], v[124:127], v[72:75]
	v_mfma_f32_16x16x32_bf16 v[80:83], v[228:231], v[152:155], v[80:83]
	s_waitcnt lgkmcnt(0)
	v_mfma_f32_16x16x32_bf16 v[84:87], v[232:235], v[124:127], v[84:87]
	v_mfma_f32_16x16x32_bf16 v[20:23], v[232:235], v[152:155], v[20:23]
	s_waitcnt vmcnt(4)
	ds_write_b128 v169, v[212:215] offset:0
	ds_write_b128 v169, v[216:219] offset:9216
	ds_write_b128 v164, v[220:223] offset:36864
	ds_write_b128 v164, v[224:227] offset:46080
	s_mov_b32 s31, s38
	s_mov_b32 s38, s39
	s_add_i32 s39, s39, 0x4800
	s_cmp_lg_u32 s39, 0xd800
	s_cselect_b32 s39, s39, 0
	s_mov_b32 s66, 0xff800000
	s_cmp_ge_u32 s5, 1
	s_cselect_b32 s66, 0x42800000, s66
	s_add_i32 s5, s5, 1
	s_add_i32 s8, s5, 2
	s_min_u32 s8, s8, 63
	s_mul_i32 s30, s8, 0xf8000
	v_add_f32_e32 v165, 0x42800000, v165
	v_add_u32_e32 v174, s31, v168
	v_add_u32_e32 v164, s39, v169
	s_add_u32 s80, s42, s30
	s_addc_u32 s81, s43, 0
	s_add_u32 s86, s80, 0x7c000
	s_addc_u32 s87, s81, 0
	s_add_u32 s96, s46, s30
	s_addc_u32 s97, s47, 0
	s_add_u32 s98, s96, 0x7c000
	s_addc_u32 s99, s97, 0
	s_waitcnt lgkmcnt(0)
	s_barrier
	s_cmp_lt_u32 s5, 64
	s_cbranch_scc1 .Ld_loopB
	v_add_u32_e32 v174, s31, v168
	ds_read_b64_tr_b16 v[228:229], v174 offset:36864
	ds_read_b64_tr_b16 v[230:231], v174 offset:41472
	ds_read_b64_tr_b16 v[232:233], v174 offset:36896
	ds_read_b64_tr_b16 v[234:235], v174 offset:41504
	ds_read_b64_tr_b16 v[236:237], v174 offset:36928
	ds_read_b64_tr_b16 v[238:239], v174 offset:41536
	ds_read_b64_tr_b16 v[240:241], v174 offset:36960
	ds_read_b64_tr_b16 v[242:243], v174 offset:41568
	ds_read_b64_tr_b16 v[244:245], v174 offset:36992
	ds_read_b64_tr_b16 v[246:247], v174 offset:41600
	v_max3_f32 v26, v88, v89, v90
	v_max3_f32 v26, v26, v91, v92
	v_max3_f32 v26, v26, v93, v94
	v_max3_f32 v26, v26, v95, v96
	v_max3_f32 v26, v26, v97, v98
	v_max3_f32 v26, v26, v99, v100
	v_max3_f32 v26, v26, v101, v102
	v_max_f32_e32 v26, v26, v103
	v_cmp_lt_f32_e32 vcc, s66, v26
	s_cbranch_vccz .Ld_nr_Bt_0
	v_mov_b32_e32 v27, v26
	s_nop 1
	v_permlane16_swap_b32_e32 v26, v27
	v_max_f32_e32 v26, v26, v27
	v_mov_b32_e32 v27, v26
	s_nop 1
	v_permlane32_swap_b32_e32 v26, v27
	v_max_f32_e32 v26, v26, v27
	v_cmp_lt_f32_e32 vcc, s66, v26
	s_nop 1
	v_cndmask_b32_e32 v3, 0, v26, vcc
	v_sub_f32_e32 v2, 0, v3
	v_min_f32_e32 v2, 0, v2
	v_exp_f32_e32 v2, v2
	v_sub_f32_e32 v24, v24, v3
	v_mul_f32_e32 v0, v0, v2
	v_mul_f32_e32 v28, v28, v2
	v_mul_f32_e32 v29, v29, v2
	v_mul_f32_e32 v30, v30, v2
	v_mul_f32_e32 v31, v31, v2
	v_mul_f32_e32 v32, v32, v2
	v_mul_f32_e32 v33, v33, v2
	v_mul_f32_e32 v34, v34, v2
	v_mul_f32_e32 v35, v35, v2
	v_mul_f32_e32 v40, v40, v2
	v_mul_f32_e32 v41, v41, v2
	v_mul_f32_e32 v42, v42, v2
	v_mul_f32_e32 v43, v43, v2
	v_mul_f32_e32 v52, v52, v2
	v_mul_f32_e32 v53, v53, v2
	v_mul_f32_e32 v54, v54, v2
	v_mul_f32_e32 v55, v55, v2
	v_mul_f32_e32 v56, v56, v2
	v_mul_f32_e32 v57, v57, v2
	v_mul_f32_e32 v58, v58, v2
	v_mul_f32_e32 v59, v59, v2
	v_mul_f32_e32 v64, v64, v2
	v_mul_f32_e32 v65, v65, v2
	v_mul_f32_e32 v66, v66, v2
	v_mul_f32_e32 v67, v67, v2
	v_mul_f32_e32 v72, v72, v2
	v_mul_f32_e32 v73, v73, v2
	v_mul_f32_e32 v74, v74, v2
	v_mul_f32_e32 v75, v75, v2
	v_mul_f32_e32 v84, v84, v2
	v_mul_f32_e32 v85, v85, v2
	v_mul_f32_e32 v86, v86, v2
	v_mul_f32_e32 v87, v87, v2
	v_sub_f32_e32 v88, v88, v3
	v_sub_f32_e32 v89, v89, v3
	v_sub_f32_e32 v90, v90, v3
	v_sub_f32_e32 v91, v91, v3
	v_sub_f32_e32 v92, v92, v3
	v_sub_f32_e32 v93, v93, v3
	v_sub_f32_e32 v94, v94, v3
	v_sub_f32_e32 v95, v95, v3
	v_sub_f32_e32 v96, v96, v3
	v_sub_f32_e32 v97, v97, v3
	v_sub_f32_e32 v98, v98, v3
	v_sub_f32_e32 v99, v99, v3
	v_sub_f32_e32 v100, v100, v3
	v_sub_f32_e32 v101, v101, v3
	v_sub_f32_e32 v102, v102, v3
	v_sub_f32_e32 v103, v103, v3

.Ld_nr_Bt_1:
	v_exp_f32_e32 v104, v104
	v_exp_f32_e32 v105, v105
	v_exp_f32_e32 v106, v106
	v_exp_f32_e32 v107, v107
	v_exp_f32_e32 v108, v108
	v_exp_f32_e32 v109, v109
	v_exp_f32_e32 v110, v110
	v_exp_f32_e32 v111, v111
	v_exp_f32_e32 v112, v112
	v_exp_f32_e32 v113, v113
	v_exp_f32_e32 v114, v114
	v_exp_f32_e32 v115, v115
	v_exp_f32_e32 v116, v116
	v_exp_f32_e32 v117, v117
	v_exp_f32_e32 v118, v118
	v_exp_f32_e32 v119, v119
	s_nop 0
	v_add_f32_e32 v26, v104, v105
	v_add_f32_e32 v26, v26, v106
	v_add_f32_e32 v26, v26, v107
	v_add_f32_e32 v26, v26, v108
	v_add_f32_e32 v26, v26, v109
	v_add_f32_e32 v26, v26, v110
	v_add_f32_e32 v26, v26, v111
	v_add_f32_e32 v26, v26, v112
	v_add_f32_e32 v26, v26, v113
	v_add_f32_e32 v26, v26, v114
	v_add_f32_e32 v26, v26, v115
	v_add_f32_e32 v26, v26, v116
	v_add_f32_e32 v26, v26, v117
	v_add_f32_e32 v26, v26, v118
	v_add_f32_e32 v26, v26, v119
	v_add_f32_e32 v151, v151, v26
	v_cvt_pk_bf16_f32 v128, v104, v105
	v_cvt_pk_bf16_f32 v129, v106, v107
	v_cvt_pk_bf16_f32 v130, v108, v109
	v_cvt_pk_bf16_f32 v131, v110, v111
	v_cvt_pk_bf16_f32 v152, v112, v113
	v_cvt_pk_bf16_f32 v153, v114, v115
	v_cvt_pk_bf16_f32 v154, v116, v117
	v_cvt_pk_bf16_f32 v155, v118, v119
	ds_read_b64_tr_b16 v[248:249], v174 offset:37024
	ds_read_b64_tr_b16 v[250:251], v174 offset:41632
	s_waitcnt lgkmcnt(10)
	v_mfma_f32_16x16x32_bf16 v[28:31], v[228:231], v[120:123], v[28:31]
	v_mfma_f32_16x16x32_bf16 v[36:39], v[228:231], v[128:131], v[36:39]
	ds_read_b64_tr_b16 v[228:229], v174 offset:37056
	ds_read_b64_tr_b16 v[230:231], v174 offset:41664
	s_waitcnt lgkmcnt(10)
	v_mfma_f32_16x16x32_bf16 v[32:35], v[232:235], v[120:123], v[32:35]
	v_mfma_f32_16x16x32_bf16 v[44:47], v[232:235], v[128:131], v[44:47]
	ds_read_b64_tr_b16 v[232:233], v174 offset:37088
	ds_read_b64_tr_b16 v[234:235], v174 offset:41696
	s_waitcnt lgkmcnt(10)
	v_mfma_f32_16x16x32_bf16 v[40:43], v[236:239], v[120:123], v[40:43]
	v_mfma_f32_16x16x32_bf16 v[48:51], v[236:239], v[128:131], v[48:51]
	ds_read_b64_tr_b16 v[236:237], v174 offset:46080
	ds_read_b64_tr_b16 v[238:239], v174 offset:50688
	s_waitcnt lgkmcnt(10)
	v_mfma_f32_16x16x32_bf16 v[52:55], v[240:243], v[120:123], v[52:55]
	v_mfma_f32_16x16x32_bf16 v[60:63], v[240:243], v[128:131], v[60:63]
	ds_read_b64_tr_b16 v[240:241], v174 offset:46112
	ds_read_b64_tr_b16 v[242:243], v174 offset:50720
	s_waitcnt lgkmcnt(10)
	v_mfma_f32_16x16x32_bf16 v[56:59], v[244:247], v[120:123], v[56:59]
	v_mfma_f32_16x16x32_bf16 v[68:71], v[244:247], v[128:131], v[68:71]
	ds_read_b64_tr_b16 v[244:245], v174 offset:46144
	ds_read_b64_tr_b16 v[246:247], v174 offset:50752
	s_waitcnt lgkmcnt(10)
	v_mfma_f32_16x16x32_bf16 v[64:67], v[248:251], v[120:123], v[64:67]
	v_mfma_f32_16x16x32_bf16 v[76:79], v[248:251], v[128:131], v[76:79]
	ds_read_b64_tr_b16 v[248:249], v174 offset:46176
	ds_read_b64_tr_b16 v[250:251], v174 offset:50784
	s_waitcnt lgkmcnt(10)
	v_mfma_f32_16x16x32_bf16 v[72:75], v[228:231], v[120:123], v[72:75]
	v_mfma_f32_16x16x32_bf16 v[80:83], v[228:231], v[128:131], v[80:83]
	ds_read_b64_tr_b16 v[228:229], v174 offset:46208
	ds_read_b64_tr_b16 v[230:231], v174 offset:50816
	s_waitcnt lgkmcnt(10)
	v_mfma_f32_16x16x32_bf16 v[84:87], v[232:235], v[120:123], v[84:87]
	v_mfma_f32_16x16x32_bf16 v[20:23], v[232:235], v[128:131], v[20:23]
	ds_read_b64_tr_b16 v[232:233], v174 offset:46240
	ds_read_b64_tr_b16 v[234:235], v174 offset:50848
	s_waitcnt lgkmcnt(10)
	v_mfma_f32_16x16x32_bf16 v[28:31], v[236:239], v[124:127], v[28:31]
	v_mfma_f32_16x16x32_bf16 v[36:39], v[236:239], v[152:155], v[36:39]
	ds_read_b64_tr_b16 v[236:237], v174 offset:46272
	ds_read_b64_tr_b16 v[238:239], v174 offset:50880
	s_waitcnt lgkmcnt(10)
	v_mfma_f32_16x16x32_bf16 v[32:35], v[240:243], v[124:127], v[32:35]
	v_mfma_f32_16x16x32_bf16 v[44:47], v[240:243], v[152:155], v[44:47]
	ds_read_b64_tr_b16 v[240:241], v174 offset:46304
	ds_read_b64_tr_b16 v[242:243], v174 offset:50912
	s_waitcnt lgkmcnt(10)
	v_mfma_f32_16x16x32_bf16 v[40:43], v[244:247], v[124:127], v[40:43]
	v_mfma_f32_16x16x32_bf16 v[48:51], v[244:247], v[152:155], v[48:51]
	s_waitcnt lgkmcnt(8)
	v_mfma_f32_16x16x32_bf16 v[52:55], v[248:251], v[124:127], v[52:55]
	v_mfma_f32_16x16x32_bf16 v[60:63], v[248:251], v[152:155], v[60:63]
	s_waitcnt lgkmcnt(6)
	v_mfma_f32_16x16x32_bf16 v[56:59], v[228:231], v[124:127], v[56:59]
	v_mfma_f32_16x16x32_bf16 v[68:71], v[228:231], v[152:155], v[68:71]
	s_waitcnt lgkmcnt(4)
	v_mfma_f32_16x16x32_bf16 v[64:67], v[232:235], v[124:127], v[64:67]
	v_mfma_f32_16x16x32_bf16 v[76:79], v[232:235], v[152:155], v[76:79]
	s_waitcnt lgkmcnt(2)
	v_mfma_f32_16x16x32_bf16 v[72:75], v[236:239], v[124:127], v[72:75]
	v_mfma_f32_16x16x32_bf16 v[80:83], v[236:239], v[152:155], v[80:83]
	s_waitcnt lgkmcnt(0)
	v_mfma_f32_16x16x32_bf16 v[84:87], v[240:243], v[124:127], v[84:87]
	v_mfma_f32_16x16x32_bf16 v[20:23], v[240:243], v[152:155], v[20:23]
	s_waitcnt vmcnt(0)
	v_mov_b32_e32 v138, 0xa00
	v_mov_b32_e32 v139, 0x0
	v_mov_b32_e32 v140, 0x9ff
	v_mov_b32_e32 v141, 0x0
	v_mov_b32_e32 v142, 0x200
	v_mov_b32_e32 v143, 0x0
	v_mov_b32_e32 v144, 0x1ff
	v_mov_b32_e32 v145, 0x0
	v_mov_b32_e32 v146, 0xb00
	v_mov_b32_e32 v147, 0x0
	v_mov_b32_e32 v148, 0xaff
	v_mov_b32_e32 v149, 0x0
	v_mov_b32_e32 v194, 0x358637bd
	v_mov_b32_e32 v195, 0x2000
	v_mov_b32_e32 v196, 0x3e38aa3b
	v_mov_b32_e32 v197, 0x41b17218
	s_branch .LBB0_634

.Ld_loopA:
	global_load_dwordx4 v[212:215], v173, s[80:81]
	global_load_dwordx4 v[220:223], v175, s[96:97]
	global_load_dwordx4 v[216:219], v173, s[86:87]
	global_load_dwordx4 v[224:227], v175, s[98:99]
	ds_read_b64_tr_b16 v[228:229], v174 offset:36864
	ds_read_b64_tr_b16 v[230:231], v174 offset:41472
	ds_read_b64_tr_b16 v[232:233], v174 offset:36896
	ds_read_b64_tr_b16 v[234:235], v174 offset:41504
	ds_read_b64_tr_b16 v[236:237], v174 offset:36928
	ds_read_b64_tr_b16 v[238:239], v174 offset:41536
	ds_read_b64_tr_b16 v[240:241], v174 offset:36960
	ds_read_b64_tr_b16 v[242:243], v174 offset:41568
	ds_read_b64_tr_b16 v[244:245], v174 offset:36992
	ds_read_b64_tr_b16 v[246:247], v174 offset:41600
	ds_read_b64_tr_b16 v[248:249], v174 offset:37024
	ds_read_b64_tr_b16 v[250:251], v174 offset:41632
	s_waitcnt lgkmcnt(10)
	v_mfma_f32_16x16x32_bf16 v[28:31], v[228:231], v[120:123], v[28:31]
	v_mfma_f32_16x16x32_bf16 v[36:39], v[228:231], v[128:131], v[36:39]
	ds_read_b64_tr_b16 v[228:229], v174 offset:37056
	ds_read_b64_tr_b16 v[230:231], v174 offset:41664
	s_waitcnt lgkmcnt(10)
	v_mfma_f32_16x16x32_bf16 v[32:35], v[232:235], v[120:123], v[32:35]
	v_mfma_f32_16x16x32_bf16 v[44:47], v[232:235], v[128:131], v[44:47]
	ds_read_b64_tr_b16 v[232:233], v174 offset:37088
	ds_read_b64_tr_b16 v[234:235], v174 offset:41696
	s_waitcnt lgkmcnt(10)
	v_mfma_f32_16x16x32_bf16 v[40:43], v[236:239], v[120:123], v[40:43]
	v_mfma_f32_16x16x32_bf16 v[48:51], v[236:239], v[128:131], v[48:51]
	ds_read_b64_tr_b16 v[236:237], v174 offset:46080
	ds_read_b64_tr_b16 v[238:239], v174 offset:50688
	s_waitcnt lgkmcnt(10)
	v_mfma_f32_16x16x32_bf16 v[52:55], v[240:243], v[120:123], v[52:55]
	v_mfma_f32_16x16x32_bf16 v[60:63], v[240:243], v[128:131], v[60:63]
	ds_read_b64_tr_b16 v[240:241], v174 offset:46112
	ds_read_b64_tr_b16 v[242:243], v174 offset:50720
	s_waitcnt lgkmcnt(10)
	v_mfma_f32_16x16x32_bf16 v[56:59], v[244:247], v[120:123], v[56:59]
	v_mfma_f32_16x16x32_bf16 v[68:71], v[244:247], v[128:131], v[68:71]
	ds_read_b64_tr_b16 v[244:245], v174 offset:46144
	ds_read_b64_tr_b16 v[246:247], v174 offset:50752
	s_waitcnt lgkmcnt(10)
	v_mfma_f32_16x16x32_bf16 v[64:67], v[248:251], v[120:123], v[64:67]
	v_mfma_f32_16x16x32_bf16 v[76:79], v[248:251], v[128:131], v[76:79]
	ds_read_b64_tr_b16 v[248:249], v174 offset:46176
	ds_read_b64_tr_b16 v[250:251], v174 offset:50784
	s_waitcnt lgkmcnt(10)
	v_mfma_f32_16x16x32_bf16 v[72:75], v[228:231], v[120:123], v[72:75]
	v_mfma_f32_16x16x32_bf16 v[80:83], v[228:231], v[128:131], v[80:83]
	ds_read_b64_tr_b16 v[228:229], v174 offset:46208
	ds_read_b64_tr_b16 v[230:231], v174 offset:50816
	s_waitcnt lgkmcnt(10)
	v_mfma_f32_16x16x32_bf16 v[84:87], v[232:235], v[120:123], v[84:87]
	v_mfma_f32_16x16x32_bf16 v[20:23], v[232:235], v[128:131], v[20:23]
	ds_read_b64_tr_b16 v[232:233], v174 offset:46240
	ds_read_b64_tr_b16 v[234:235], v174 offset:50848
	s_waitcnt lgkmcnt(10)
	v_mfma_f32_16x16x32_bf16 v[28:31], v[236:239], v[124:127], v[28:31]
	v_mfma_f32_16x16x32_bf16 v[36:39], v[236:239], v[152:155], v[36:39]
	ds_read_b64_tr_b16 v[236:237], v174 offset:46272
	ds_read_b64_tr_b16 v[238:239], v174 offset:50880
	s_waitcnt lgkmcnt(10)
	v_mfma_f32_16x16x32_bf16 v[32:35], v[240:243], v[124:127], v[32:35]
	v_mfma_f32_16x16x32_bf16 v[44:47], v[240:243], v[152:155], v[44:47]
	ds_read_b64_tr_b16 v[240:241], v174 offset:46304
	ds_read_b64_tr_b16 v[242:243], v174 offset:50912
	s_waitcnt lgkmcnt(10)
	v_mfma_f32_16x16x32_bf16 v[40:43], v[244:247], v[124:127], v[40:43]
	v_mfma_f32_16x16x32_bf16 v[48:51], v[244:247], v[152:155], v[48:51]
	ds_read_b128 v[244:247], v255 offset:0
	s_waitcnt lgkmcnt(9)
	v_mfma_f32_16x16x32_bf16 v[52:55], v[248:251], v[124:127], v[52:55]
	v_mfma_f32_16x16x32_bf16 v[60:63], v[248:251], v[152:155], v[60:63]
	ds_read_b128 v[248:251], v255 offset:64
	s_waitcnt lgkmcnt(8)
	v_mfma_f32_16x16x32_bf16 v[56:59], v[228:231], v[124:127], v[56:59]
	v_mfma_f32_16x16x32_bf16 v[68:71], v[228:231], v[152:155], v[68:71]
	ds_read_b128 v[228:231], v255 offset:4608
	s_waitcnt lgkmcnt(7)
	v_mfma_f32_16x16x32_bf16 v[64:67], v[232:235], v[124:127], v[64:67]
	v_mfma_f32_16x16x32_bf16 v[76:79], v[232:235], v[152:155], v[76:79]
	ds_read_b128 v[232:235], v255 offset:4672
	s_waitcnt lgkmcnt(6)
	v_mfma_f32_16x16x32_bf16 v[72:75], v[236:239], v[124:127], v[72:75]
	v_mfma_f32_16x16x32_bf16 v[80:83], v[236:239], v[152:155], v[80:83]
	ds_read_b128 v[236:239], v255 offset:9216
	s_waitcnt lgkmcnt(5)
	v_mfma_f32_16x16x32_bf16 v[84:87], v[240:243], v[124:127], v[84:87]
	v_mfma_f32_16x16x32_bf16 v[20:23], v[240:243], v[152:155], v[20:23]
	ds_read_b128 v[240:243], v255 offset:9280
	s_waitcnt lgkmcnt(5)
	v_mfma_f32_16x16x32_bf16 v[88:91], v[244:247], v[4:7], v[156:159]
	ds_read_b128 v[244:247], v255 offset:13824
	s_waitcnt lgkmcnt(5)
	v_mfma_f32_16x16x32_bf16 v[88:91], v[248:251], v[8:11], v[88:91]
	ds_read_b128 v[248:251], v255 offset:13888
	s_waitcnt lgkmcnt(5)
	v_mfma_f32_16x16x32_bf16 v[92:95], v[228:231], v[4:7], v[160:163]
	ds_read_b128 v[228:231], v255 offset:128
	s_waitcnt lgkmcnt(5)
	v_mfma_f32_16x16x32_bf16 v[92:95], v[232:235], v[8:11], v[92:95]
	ds_read_b128 v[232:235], v255 offset:192
	s_waitcnt lgkmcnt(5)
	v_mfma_f32_16x16x32_bf16 v[96:99], v[236:239], v[4:7], v[176:179]
	ds_read_b128 v[236:239], v255 offset:4736
	s_waitcnt lgkmcnt(5)
	v_mfma_f32_16x16x32_bf16 v[96:99], v[240:243], v[8:11], v[96:99]
	ds_read_b128 v[240:243], v255 offset:4800
	s_waitcnt lgkmcnt(5)
	v_mfma_f32_16x16x32_bf16 v[100:103], v[244:247], v[4:7], v[180:183]
	ds_read_b128 v[244:247], v255 offset:9344
	s_waitcnt lgkmcnt(5)
	v_mfma_f32_16x16x32_bf16 v[100:103], v[248:251], v[8:11], v[100:103]
	ds_read_b128 v[248:251], v255 offset:9408
	s_waitcnt lgkmcnt(5)
	v_mfma_f32_16x16x32_bf16 v[104:107], v[228:231], v[12:15], v[204:207]
	ds_read_b128 v[228:231], v255 offset:13952
	s_waitcnt lgkmcnt(5)
	v_mfma_f32_16x16x32_bf16 v[104:107], v[232:235], v[16:19], v[104:107]
	ds_read_b128 v[232:235], v255 offset:14016
	s_waitcnt lgkmcnt(5)
	v_mfma_f32_16x16x32_bf16 v[108:111], v[236:239], v[12:15], v[208:211]
	s_waitcnt lgkmcnt(4)
	v_mfma_f32_16x16x32_bf16 v[108:111], v[240:243], v[16:19], v[108:111]
	s_waitcnt lgkmcnt(3)
	v_mfma_f32_16x16x32_bf16 v[112:115], v[244:247], v[12:15], v[184:187]
	s_waitcnt lgkmcnt(2)
	v_mfma_f32_16x16x32_bf16 v[112:115], v[248:251], v[16:19], v[112:115]
	s_waitcnt lgkmcnt(1)
	v_mfma_f32_16x16x32_bf16 v[116:119], v[228:231], v[12:15], v[188:191]
	s_waitcnt lgkmcnt(0)
	v_mfma_f32_16x16x32_bf16 v[116:119], v[232:235], v[16:19], v[116:119]
	v_max3_f32 v26, v88, v89, v90
	v_max3_f32 v26, v26, v91, v92
	v_max3_f32 v26, v26, v93, v94
	v_max3_f32 v26, v26, v95, v96
	v_max3_f32 v26, v26, v97, v98
	v_max3_f32 v26, v26, v99, v100
	v_max3_f32 v26, v26, v101, v102
	v_max_f32_e32 v26, v26, v103
	v_cmp_lt_f32_e32 vcc, s66, v26
	s_cbranch_vccz .Ld_nr_A0_0
	v_mov_b32_e32 v27, v26
	s_nop 1
	v_permlane16_swap_b32_e32 v26, v27
	v_max_f32_e32 v26, v26, v27
	v_mov_b32_e32 v27, v26
	s_nop 1
	v_permlane32_swap_b32_e32 v26, v27
	v_max_f32_e32 v26, v26, v27
	v_cmp_lt_f32_e32 vcc, s66, v26
	s_nop 1
	v_cndmask_b32_e32 v3, 0, v26, vcc
	v_sub_f32_e32 v2, 0, v3
	v_min_f32_e32 v2, 0, v2
	v_exp_f32_e32 v2, v2
	v_sub_f32_e32 v24, v24, v3
	v_mul_f32_e32 v0, v0, v2
	v_mul_f32_e32 v28, v28, v2
	v_mul_f32_e32 v29, v29, v2
	v_mul_f32_e32 v30, v30, v2
	v_mul_f32_e32 v31, v31, v2
	v_mul_f32_e32 v32, v32, v2
	v_mul_f32_e32 v33, v33, v2
	v_mul_f32_e32 v34, v34, v2
	v_mul_f32_e32 v35, v35, v2
	v_mul_f32_e32 v40, v40, v2
	v_mul_f32_e32 v41, v41, v2
	v_mul_f32_e32 v42, v42, v2
	v_mul_f32_e32 v43, v43, v2
	v_mul_f32_e32 v52, v52, v2
	v_mul_f32_e32 v53, v53, v2
	v_mul_f32_e32 v54, v54, v2
	v_mul_f32_e32 v55, v55, v2
	v_mul_f32_e32 v56, v56, v2
	v_mul_f32_e32 v57, v57, v2
	v_mul_f32_e32 v58, v58, v2
	v_mul_f32_e32 v59, v59, v2
	v_mul_f32_e32 v64, v64, v2
	v_mul_f32_e32 v65, v65, v2
	v_mul_f32_e32 v66, v66, v2
	v_mul_f32_e32 v67, v67, v2
	v_mul_f32_e32 v72, v72, v2
	v_mul_f32_e32 v73, v73, v2
	v_mul_f32_e32 v74, v74, v2
	v_mul_f32_e32 v75, v75, v2
	v_mul_f32_e32 v84, v84, v2
	v_mul_f32_e32 v85, v85, v2
	v_mul_f32_e32 v86, v86, v2
	v_mul_f32_e32 v87, v87, v2
	v_sub_f32_e32 v88, v88, v3
	v_sub_f32_e32 v89, v89, v3
	v_sub_f32_e32 v90, v90, v3
	v_sub_f32_e32 v91, v91, v3
	v_sub_f32_e32 v92, v92, v3
	v_sub_f32_e32 v93, v93, v3
	v_sub_f32_e32 v94, v94, v3
	v_sub_f32_e32 v95, v95, v3
	v_sub_f32_e32 v96, v96, v3
	v_sub_f32_e32 v97, v97, v3
	v_sub_f32_e32 v98, v98, v3
	v_sub_f32_e32 v99, v99, v3
	v_sub_f32_e32 v100, v100, v3
	v_sub_f32_e32 v101, v101, v3
	v_sub_f32_e32 v102, v102, v3
	v_sub_f32_e32 v103, v103, v3

.Ld_nr_A0_1:
	v_exp_f32_e32 v104, v104
	v_exp_f32_e32 v105, v105
	v_exp_f32_e32 v106, v106
	v_exp_f32_e32 v107, v107
	v_exp_f32_e32 v108, v108
	v_exp_f32_e32 v109, v109
	v_exp_f32_e32 v110, v110
	v_exp_f32_e32 v111, v111
	v_exp_f32_e32 v112, v112
	v_exp_f32_e32 v113, v113
	v_exp_f32_e32 v114, v114
	v_exp_f32_e32 v115, v115
	v_exp_f32_e32 v116, v116
	v_exp_f32_e32 v117, v117
	v_exp_f32_e32 v118, v118
	v_exp_f32_e32 v119, v119
	s_nop 0
	v_add_f32_e32 v26, v104, v105
	v_add_f32_e32 v26, v26, v106
	v_add_f32_e32 v26, v26, v107
	v_add_f32_e32 v26, v26, v108
	v_add_f32_e32 v26, v26, v109
	v_add_f32_e32 v26, v26, v110
	v_add_f32_e32 v26, v26, v111
	v_add_f32_e32 v26, v26, v112
	v_add_f32_e32 v26, v26, v113
	v_add_f32_e32 v26, v26, v114
	v_add_f32_e32 v26, v26, v115
	v_add_f32_e32 v26, v26, v116
	v_add_f32_e32 v26, v26, v117
	v_add_f32_e32 v26, v26, v118
	v_add_f32_e32 v26, v26, v119
	v_add_f32_e32 v151, v151, v26
	v_cvt_pk_bf16_f32 v128, v104, v105
	v_cvt_pk_bf16_f32 v129, v106, v107
	v_cvt_pk_bf16_f32 v130, v108, v109
	v_cvt_pk_bf16_f32 v131, v110, v111
	v_cvt_pk_bf16_f32 v152, v112, v113
	v_cvt_pk_bf16_f32 v153, v114, v115
	v_cvt_pk_bf16_f32 v154, v116, v117
	v_cvt_pk_bf16_f32 v155, v118, v119
	v_add_f32_e32 v165, 0x42800000, v165
	v_mov_b32_e32 v156, v165
	v_add_f32_e32 v157, 0x3f800000, v165
	v_add_f32_e32 v158, 0x40000000, v165
	v_add_f32_e32 v159, 0x40400000, v165
	v_add_f32_e32 v160, 0x41800000, v165
	v_add_f32_e32 v161, 0x41880000, v165
	v_add_f32_e32 v162, 0x41900000, v165
	v_add_f32_e32 v163, 0x41980000, v165
	v_add_f32_e32 v176, 0x42000000, v165
	v_add_f32_e32 v177, 0x42040000, v165
	v_add_f32_e32 v178, 0x42080000, v165
	v_add_f32_e32 v179, 0x420c0000, v165
	v_add_f32_e32 v180, 0x42400000, v165
	v_add_f32_e32 v181, 0x42440000, v165
	v_add_f32_e32 v182, 0x42480000, v165
	v_add_f32_e32 v183, 0x424c0000, v165
	v_fma_f32 v204, -v150, |v156|, v25
	v_fma_f32 v205, -v150, |v157|, v25
	v_fma_f32 v206, -v150, |v158|, v25
	v_fma_f32 v207, -v150, |v159|, v25
	v_fma_f32 v208, -v150, |v160|, v25
	v_fma_f32 v209, -v150, |v161|, v25
	v_fma_f32 v210, -v150, |v162|, v25
	v_fma_f32 v211, -v150, |v163|, v25
	v_fma_f32 v184, -v150, |v176|, v25
	v_fma_f32 v185, -v150, |v177|, v25
	v_fma_f32 v186, -v150, |v178|, v25
	v_fma_f32 v187, -v150, |v179|, v25
	v_fma_f32 v188, -v150, |v180|, v25
	v_fma_f32 v189, -v150, |v181|, v25
	v_fma_f32 v190, -v150, |v182|, v25
	v_fma_f32 v191, -v150, |v183|, v25
	v_fma_f32 v156, -v150, |v156|, v24
	v_fma_f32 v157, -v150, |v157|, v24
	v_fma_f32 v158, -v150, |v158|, v24
	v_fma_f32 v159, -v150, |v159|, v24
	v_fma_f32 v160, -v150, |v160|, v24
	v_fma_f32 v161, -v150, |v161|, v24
	v_fma_f32 v162, -v150, |v162|, v24
	v_fma_f32 v163, -v150, |v163|, v24
	v_fma_f32 v176, -v150, |v176|, v24
	v_fma_f32 v177, -v150, |v177|, v24
	v_fma_f32 v178, -v150, |v178|, v24
	v_fma_f32 v179, -v150, |v179|, v24
	v_fma_f32 v180, -v150, |v180|, v24
	v_fma_f32 v181, -v150, |v181|, v24
	v_fma_f32 v182, -v150, |v182|, v24
	v_fma_f32 v183, -v150, |v183|, v24
	s_waitcnt vmcnt(4)
	ds_write_b128 v169, v[138:141] offset:18432
	ds_write_b128 v169, v[142:145] offset:27648
	ds_write_b128 v164, v[146:149] offset:36864
	ds_write_b128 v164, v[194:197] offset:46080
	s_mov_b32 s31, s38
	s_mov_b32 s38, s39
	s_add_i32 s39, s39, 0x4800
	s_cmp_lg_u32 s39, 0xd800
	s_cselect_b32 s39, s39, 0
	s_mov_b32 s66, 0x42800000
	s_add_i32 s5, s5, 1
	s_add_i32 s8, s5, 2
	s_min_u32 s8, s8, 63
	s_mul_i32 s30, s8, 0xf8000
	v_add_u32_e32 v174, s31, v168
	v_add_u32_e32 v164, s39, v169
	s_add_u32 s80, s42, s30
	s_addc_u32 s81, s43, 0
	s_add_u32 s86, s80, 0x7c000
	s_addc_u32 s87, s81, 0
	s_add_u32 s96, s46, s30
	s_addc_u32 s97, s47, 0
	s_add_u32 s98, s96, 0x7c000
	s_addc_u32 s99, s97, 0
	s_waitcnt lgkmcnt(0)
	s_barrier
	global_load_dwordx4 v[138:141], v173, s[80:81]
	global_load_dwordx4 v[146:149], v175, s[96:97]
	global_load_dwordx4 v[142:145], v173, s[86:87]
	global_load_dwordx4 v[194:197], v175, s[98:99]
	ds_read_b64_tr_b16 v[228:229], v174 offset:36864
	ds_read_b64_tr_b16 v[230:231], v174 offset:41472
	ds_read_b64_tr_b16 v[232:233], v174 offset:36896
	ds_read_b64_tr_b16 v[234:235], v174 offset:41504
	ds_read_b64_tr_b16 v[236:237], v174 offset:36928
	ds_read_b64_tr_b16 v[238:239], v174 offset:41536
	ds_read_b64_tr_b16 v[240:241], v174 offset:36960
	ds_read_b64_tr_b16 v[242:243], v174 offset:41568
	ds_read_b64_tr_b16 v[244:245], v174 offset:36992
	ds_read_b64_tr_b16 v[246:247], v174 offset:41600
	ds_read_b64_tr_b16 v[248:249], v174 offset:37024
	ds_read_b64_tr_b16 v[250:251], v174 offset:41632
	s_waitcnt lgkmcnt(10)
	v_mfma_f32_16x16x32_bf16 v[28:31], v[228:231], v[120:123], v[28:31]
	v_mfma_f32_16x16x32_bf16 v[36:39], v[228:231], v[128:131], v[36:39]
	ds_read_b64_tr_b16 v[228:229], v174 offset:37056
	ds_read_b64_tr_b16 v[230:231], v174 offset:41664
	s_waitcnt lgkmcnt(10)
	v_mfma_f32_16x16x32_bf16 v[32:35], v[232:235], v[120:123], v[32:35]
	v_mfma_f32_16x16x32_bf16 v[44:47], v[232:235], v[128:131], v[44:47]
	ds_read_b64_tr_b16 v[232:233], v174 offset:37088
	ds_read_b64_tr_b16 v[234:235], v174 offset:41696
	s_waitcnt lgkmcnt(10)
	v_mfma_f32_16x16x32_bf16 v[40:43], v[236:239], v[120:123], v[40:43]
	v_mfma_f32_16x16x32_bf16 v[48:51], v[236:239], v[128:131], v[48:51]
	ds_read_b64_tr_b16 v[236:237], v174 offset:46080
	ds_read_b64_tr_b16 v[238:239], v174 offset:50688
	s_waitcnt lgkmcnt(10)
	v_mfma_f32_16x16x32_bf16 v[52:55], v[240:243], v[120:123], v[52:55]
	v_mfma_f32_16x16x32_bf16 v[60:63], v[240:243], v[128:131], v[60:63]
	ds_read_b64_tr_b16 v[240:241], v174 offset:46112
	ds_read_b64_tr_b16 v[242:243], v174 offset:50720
	s_waitcnt lgkmcnt(10)
	v_mfma_f32_16x16x32_bf16 v[56:59], v[244:247], v[120:123], v[56:59]
	v_mfma_f32_16x16x32_bf16 v[68:71], v[244:247], v[128:131], v[68:71]
	ds_read_b64_tr_b16 v[244:245], v174 offset:46144
	ds_read_b64_tr_b16 v[246:247], v174 offset:50752
	s_waitcnt lgkmcnt(10)
	v_mfma_f32_16x16x32_bf16 v[64:67], v[248:251], v[120:123], v[64:67]
	v_mfma_f32_16x16x32_bf16 v[76:79], v[248:251], v[128:131], v[76:79]
	ds_read_b64_tr_b16 v[248:249], v174 offset:46176
	ds_read_b64_tr_b16 v[250:251], v174 offset:50784
	s_waitcnt lgkmcnt(10)
	v_mfma_f32_16x16x32_bf16 v[72:75], v[228:231], v[120:123], v[72:75]
	v_mfma_f32_16x16x32_bf16 v[80:83], v[228:231], v[128:131], v[80:83]
	ds_read_b64_tr_b16 v[228:229], v174 offset:46208
	ds_read_b64_tr_b16 v[230:231], v174 offset:50816
	s_waitcnt lgkmcnt(10)
	v_mfma_f32_16x16x32_bf16 v[84:87], v[232:235], v[120:123], v[84:87]
	v_mfma_f32_16x16x32_bf16 v[20:23], v[232:235], v[128:131], v[20:23]
	ds_read_b64_tr_b16 v[232:233], v174 offset:46240
	ds_read_b64_tr_b16 v[234:235], v174 offset:50848
	s_waitcnt lgkmcnt(10)
	v_mfma_f32_16x16x32_bf16 v[28:31], v[236:239], v[124:127], v[28:31]
	v_mfma_f32_16x16x32_bf16 v[36:39], v[236:239], v[152:155], v[36:39]
	ds_read_b64_tr_b16 v[236:237], v174 offset:46272
	ds_read_b64_tr_b16 v[238:239], v174 offset:50880
	s_waitcnt lgkmcnt(10)
	v_mfma_f32_16x16x32_bf16 v[32:35], v[240:243], v[124:127], v[32:35]
	v_mfma_f32_16x16x32_bf16 v[44:47], v[240:243], v[152:155], v[44:47]
	ds_read_b64_tr_b16 v[240:241], v174 offset:46304
	ds_read_b64_tr_b16 v[242:243], v174 offset:50912
	s_waitcnt lgkmcnt(10)
	v_mfma_f32_16x16x32_bf16 v[40:43], v[244:247], v[124:127], v[40:43]
	v_mfma_f32_16x16x32_bf16 v[48:51], v[244:247], v[152:155], v[48:51]
	ds_read_b128 v[244:247], v255 offset:18432
	s_waitcnt lgkmcnt(9)
	v_mfma_f32_16x16x32_bf16 v[52:55], v[248:251], v[124:127], v[52:55]
	v_mfma_f32_16x16x32_bf16 v[60:63], v[248:251], v[152:155], v[60:63]
	ds_read_b128 v[248:251], v255 offset:18496
	s_waitcnt lgkmcnt(8)
	v_mfma_f32_16x16x32_bf16 v[56:59], v[228:231], v[124:127], v[56:59]
	v_mfma_f32_16x16x32_bf16 v[68:71], v[228:231], v[152:155], v[68:71]
	ds_read_b128 v[228:231], v255 offset:23040
	s_waitcnt lgkmcnt(7)
	v_mfma_f32_16x16x32_bf16 v[64:67], v[232:235], v[124:127], v[64:67]
	v_mfma_f32_16x16x32_bf16 v[76:79], v[232:235], v[152:155], v[76:79]
	ds_read_b128 v[232:235], v255 offset:23104
	s_waitcnt lgkmcnt(6)
	v_mfma_f32_16x16x32_bf16 v[72:75], v[236:239], v[124:127], v[72:75]
	v_mfma_f32_16x16x32_bf16 v[80:83], v[236:239], v[152:155], v[80:83]
	ds_read_b128 v[236:239], v255 offset:27648
	s_waitcnt lgkmcnt(5)
	v_mfma_f32_16x16x32_bf16 v[84:87], v[240:243], v[124:127], v[84:87]
	v_mfma_f32_16x16x32_bf16 v[20:23], v[240:243], v[152:155], v[20:23]
	ds_read_b128 v[240:243], v255 offset:27712
	s_waitcnt lgkmcnt(5)
	v_mfma_f32_16x16x32_bf16 v[88:91], v[244:247], v[4:7], v[156:159]
	ds_read_b128 v[244:247], v255 offset:32256
	s_waitcnt lgkmcnt(5)
	v_mfma_f32_16x16x32_bf16 v[88:91], v[248:251], v[8:11], v[88:91]
	ds_read_b128 v[248:251], v255 offset:32320
	s_waitcnt lgkmcnt(5)
	v_mfma_f32_16x16x32_bf16 v[92:95], v[228:231], v[4:7], v[160:163]
	ds_read_b128 v[228:231], v255 offset:18560
	s_waitcnt lgkmcnt(5)
	v_mfma_f32_16x16x32_bf16 v[92:95], v[232:235], v[8:11], v[92:95]
	ds_read_b128 v[232:235], v255 offset:18624
	s_waitcnt lgkmcnt(5)
	v_mfma_f32_16x16x32_bf16 v[96:99], v[236:239], v[4:7], v[176:179]
	ds_read_b128 v[236:239], v255 offset:23168
	s_waitcnt lgkmcnt(5)
	v_mfma_f32_16x16x32_bf16 v[96:99], v[240:243], v[8:11], v[96:99]
	ds_read_b128 v[240:243], v255 offset:23232
	s_waitcnt lgkmcnt(5)
	v_mfma_f32_16x16x32_bf16 v[100:103], v[244:247], v[4:7], v[180:183]
	ds_read_b128 v[244:247], v255 offset:27776
	s_waitcnt lgkmcnt(5)
	v_mfma_f32_16x16x32_bf16 v[100:103], v[248:251], v[8:11], v[100:103]
	ds_read_b128 v[248:251], v255 offset:27840
	s_waitcnt lgkmcnt(5)
	v_mfma_f32_16x16x32_bf16 v[104:107], v[228:231], v[12:15], v[204:207]
	ds_read_b128 v[228:231], v255 offset:32384
	s_waitcnt lgkmcnt(5)
	v_mfma_f32_16x16x32_bf16 v[104:107], v[232:235], v[16:19], v[104:107]
	ds_read_b128 v[232:235], v255 offset:32448
	s_waitcnt lgkmcnt(5)
	v_mfma_f32_16x16x32_bf16 v[108:111], v[236:239], v[12:15], v[208:211]
	s_waitcnt lgkmcnt(4)
	v_mfma_f32_16x16x32_bf16 v[108:111], v[240:243], v[16:19], v[108:111]
	s_waitcnt lgkmcnt(3)
	v_mfma_f32_16x16x32_bf16 v[112:115], v[244:247], v[12:15], v[184:187]
	s_waitcnt lgkmcnt(2)
	v_mfma_f32_16x16x32_bf16 v[112:115], v[248:251], v[16:19], v[112:115]
	s_waitcnt lgkmcnt(1)
	v_mfma_f32_16x16x32_bf16 v[116:119], v[228:231], v[12:15], v[188:191]
	s_waitcnt lgkmcnt(0)
	v_mfma_f32_16x16x32_bf16 v[116:119], v[232:235], v[16:19], v[116:119]
	v_max3_f32 v26, v88, v89, v90
	v_max3_f32 v26, v26, v91, v92
	v_max3_f32 v26, v26, v93, v94
	v_max3_f32 v26, v26, v95, v96
	v_max3_f32 v26, v26, v97, v98
	v_max3_f32 v26, v26, v99, v100
	v_max3_f32 v26, v26, v101, v102
	v_max_f32_e32 v26, v26, v103
	v_cmp_lt_f32_e32 vcc, s66, v26
	s_cbranch_vccz .Ld_nr_A1_0
	v_mov_b32_e32 v27, v26
	s_nop 1
	v_permlane16_swap_b32_e32 v26, v27
	v_max_f32_e32 v26, v26, v27
	v_mov_b32_e32 v27, v26
	s_nop 1
	v_permlane32_swap_b32_e32 v26, v27
	v_max_f32_e32 v26, v26, v27
	v_cmp_lt_f32_e32 vcc, s66, v26
	s_nop 1
	v_cndmask_b32_e32 v3, 0, v26, vcc
	v_sub_f32_e32 v2, 0, v3
	v_min_f32_e32 v2, 0, v2
	v_exp_f32_e32 v2, v2
	v_sub_f32_e32 v24, v24, v3
	v_mul_f32_e32 v0, v0, v2
	v_mul_f32_e32 v28, v28, v2
	v_mul_f32_e32 v29, v29, v2
	v_mul_f32_e32 v30, v30, v2
	v_mul_f32_e32 v31, v31, v2
	v_mul_f32_e32 v32, v32, v2
	v_mul_f32_e32 v33, v33, v2
	v_mul_f32_e32 v34, v34, v2
	v_mul_f32_e32 v35, v35, v2
	v_mul_f32_e32 v40, v40, v2
	v_mul_f32_e32 v41, v41, v2
	v_mul_f32_e32 v42, v42, v2
	v_mul_f32_e32 v43, v43, v2
	v_mul_f32_e32 v52, v52, v2
	v_mul_f32_e32 v53, v53, v2
	v_mul_f32_e32 v54, v54, v2
	v_mul_f32_e32 v55, v55, v2
	v_mul_f32_e32 v56, v56, v2
	v_mul_f32_e32 v57, v57, v2
	v_mul_f32_e32 v58, v58, v2
	v_mul_f32_e32 v59, v59, v2
	v_mul_f32_e32 v64, v64, v2
	v_mul_f32_e32 v65, v65, v2
	v_mul_f32_e32 v66, v66, v2
	v_mul_f32_e32 v67, v67, v2
	v_mul_f32_e32 v72, v72, v2
	v_mul_f32_e32 v73, v73, v2
	v_mul_f32_e32 v74, v74, v2
	v_mul_f32_e32 v75, v75, v2
	v_mul_f32_e32 v84, v84, v2
	v_mul_f32_e32 v85, v85, v2
	v_mul_f32_e32 v86, v86, v2
	v_mul_f32_e32 v87, v87, v2
	v_sub_f32_e32 v88, v88, v3
	v_sub_f32_e32 v89, v89, v3
	v_sub_f32_e32 v90, v90, v3
	v_sub_f32_e32 v91, v91, v3
	v_sub_f32_e32 v92, v92, v3
	v_sub_f32_e32 v93, v93, v3
	v_sub_f32_e32 v94, v94, v3
	v_sub_f32_e32 v95, v95, v3
	v_sub_f32_e32 v96, v96, v3
	v_sub_f32_e32 v97, v97, v3
	v_sub_f32_e32 v98, v98, v3
	v_sub_f32_e32 v99, v99, v3
	v_sub_f32_e32 v100, v100, v3
	v_sub_f32_e32 v101, v101, v3
	v_sub_f32_e32 v102, v102, v3
	v_sub_f32_e32 v103, v103, v3

.Ld_nr_A1_1:
	v_exp_f32_e32 v104, v104
	v_exp_f32_e32 v105, v105
	v_exp_f32_e32 v106, v106
	v_exp_f32_e32 v107, v107
	v_exp_f32_e32 v108, v108
	v_exp_f32_e32 v109, v109
	v_exp_f32_e32 v110, v110
	v_exp_f32_e32 v111, v111
	v_exp_f32_e32 v112, v112
	v_exp_f32_e32 v113, v113
	v_exp_f32_e32 v114, v114
	v_exp_f32_e32 v115, v115
	v_exp_f32_e32 v116, v116
	v_exp_f32_e32 v117, v117
	v_exp_f32_e32 v118, v118
	v_exp_f32_e32 v119, v119
	s_nop 0
	v_add_f32_e32 v26, v104, v105
	v_add_f32_e32 v26, v26, v106
	v_add_f32_e32 v26, v26, v107
	v_add_f32_e32 v26, v26, v108
	v_add_f32_e32 v26, v26, v109
	v_add_f32_e32 v26, v26, v110
	v_add_f32_e32 v26, v26, v111
	v_add_f32_e32 v26, v26, v112
	v_add_f32_e32 v26, v26, v113
	v_add_f32_e32 v26, v26, v114
	v_add_f32_e32 v26, v26, v115
	v_add_f32_e32 v26, v26, v116
	v_add_f32_e32 v26, v26, v117
	v_add_f32_e32 v26, v26, v118
	v_add_f32_e32 v26, v26, v119
	v_add_f32_e32 v151, v151, v26
	v_cvt_pk_bf16_f32 v128, v104, v105
	v_cvt_pk_bf16_f32 v129, v106, v107
	v_cvt_pk_bf16_f32 v130, v108, v109
	v_cvt_pk_bf16_f32 v131, v110, v111
	v_cvt_pk_bf16_f32 v152, v112, v113
	v_cvt_pk_bf16_f32 v153, v114, v115
	v_cvt_pk_bf16_f32 v154, v116, v117
	v_cvt_pk_bf16_f32 v155, v118, v119
	v_add_f32_e32 v165, 0x42800000, v165
	v_mov_b32_e32 v156, v165
	v_add_f32_e32 v157, 0x3f800000, v165
	v_add_f32_e32 v158, 0x40000000, v165
	v_add_f32_e32 v159, 0x40400000, v165
	v_add_f32_e32 v160, 0x41800000, v165
	v_add_f32_e32 v161, 0x41880000, v165
	v_add_f32_e32 v162, 0x41900000, v165
	v_add_f32_e32 v163, 0x41980000, v165
	v_add_f32_e32 v176, 0x42000000, v165
	v_add_f32_e32 v177, 0x42040000, v165
	v_add_f32_e32 v178, 0x42080000, v165
	v_add_f32_e32 v179, 0x420c0000, v165
	v_add_f32_e32 v180, 0x42400000, v165
	v_add_f32_e32 v181, 0x42440000, v165
	v_add_f32_e32 v182, 0x42480000, v165
	v_add_f32_e32 v183, 0x424c0000, v165
	v_fma_f32 v204, -v150, |v156|, v25
	v_fma_f32 v205, -v150, |v157|, v25
	v_fma_f32 v206, -v150, |v158|, v25
	v_fma_f32 v207, -v150, |v159|, v25
	v_fma_f32 v208, -v150, |v160|, v25
	v_fma_f32 v209, -v150, |v161|, v25
	v_fma_f32 v210, -v150, |v162|, v25
	v_fma_f32 v211, -v150, |v163|, v25
	v_fma_f32 v184, -v150, |v176|, v25
	v_fma_f32 v185, -v150, |v177|, v25
	v_fma_f32 v186, -v150, |v178|, v25
	v_fma_f32 v187, -v150, |v179|, v25
	v_fma_f32 v188, -v150, |v180|, v25
	v_fma_f32 v189, -v150, |v181|, v25
	v_fma_f32 v190, -v150, |v182|, v25
	v_fma_f32 v191, -v150, |v183|, v25
	v_fma_f32 v156, -v150, |v156|, v24
	v_fma_f32 v157, -v150, |v157|, v24
	v_fma_f32 v158, -v150, |v158|, v24
	v_fma_f32 v159, -v150, |v159|, v24
	v_fma_f32 v160, -v150, |v160|, v24
	v_fma_f32 v161, -v150, |v161|, v24
	v_fma_f32 v162, -v150, |v162|, v24
	v_fma_f32 v163, -v150, |v163|, v24
	v_fma_f32 v176, -v150, |v176|, v24
	v_fma_f32 v177, -v150, |v177|, v24
	v_fma_f32 v178, -v150, |v178|, v24
	v_fma_f32 v179, -v150, |v179|, v24
	v_fma_f32 v180, -v150, |v180|, v24
	v_fma_f32 v181, -v150, |v181|, v24
	v_fma_f32 v182, -v150, |v182|, v24
	v_fma_f32 v183, -v150, |v183|, v24
	s_waitcnt vmcnt(4)
	ds_write_b128 v169, v[212:215] offset:0
	ds_write_b128 v169, v[216:219] offset:9216
	ds_write_b128 v164, v[220:223] offset:36864
	ds_write_b128 v164, v[224:227] offset:46080
	s_mov_b32 s31, s38
	s_mov_b32 s38, s39
	s_add_i32 s39, s39, 0x4800
	s_cmp_lg_u32 s39, 0xd800
	s_cselect_b32 s39, s39, 0
	s_mov_b32 s66, 0x42800000
	s_add_i32 s5, s5, 1
	s_add_i32 s8, s5, 2
	s_min_u32 s8, s8, 63
	s_mul_i32 s30, s8, 0xf8000
	v_add_u32_e32 v174, s31, v168
	v_add_u32_e32 v164, s39, v169
	s_add_u32 s80, s42, s30
	s_addc_u32 s81, s43, 0
	s_add_u32 s86, s80, 0x7c000
	s_addc_u32 s87, s81, 0
	s_add_u32 s96, s46, s30
	s_addc_u32 s97, s47, 0
	s_add_u32 s98, s96, 0x7c000
	s_addc_u32 s99, s97, 0
	s_waitcnt lgkmcnt(0)
	s_barrier
	s_cmp_lt_u32 s5, 64
	s_cbranch_scc1 .Ld_loopA
	v_add_u32_e32 v174, s31, v168
	ds_read_b64_tr_b16 v[228:229], v174 offset:36864
	ds_read_b64_tr_b16 v[230:231], v174 offset:41472
	ds_read_b64_tr_b16 v[232:233], v174 offset:36896
	ds_read_b64_tr_b16 v[234:235], v174 offset:41504
	ds_read_b64_tr_b16 v[236:237], v174 offset:36928
	ds_read_b64_tr_b16 v[238:239], v174 offset:41536
	ds_read_b64_tr_b16 v[240:241], v174 offset:36960
	ds_read_b64_tr_b16 v[242:243], v174 offset:41568
	ds_read_b64_tr_b16 v[244:245], v174 offset:36992
	ds_read_b64_tr_b16 v[246:247], v174 offset:41600
	ds_read_b64_tr_b16 v[248:249], v174 offset:37024
	ds_read_b64_tr_b16 v[250:251], v174 offset:41632
	s_waitcnt lgkmcnt(10)
	v_mfma_f32_16x16x32_bf16 v[28:31], v[228:231], v[120:123], v[28:31]
	v_mfma_f32_16x16x32_bf16 v[36:39], v[228:231], v[128:131], v[36:39]
	ds_read_b64_tr_b16 v[228:229], v174 offset:37056
	ds_read_b64_tr_b16 v[230:231], v174 offset:41664
	s_waitcnt lgkmcnt(10)
	v_mfma_f32_16x16x32_bf16 v[32:35], v[232:235], v[120:123], v[32:35]
	v_mfma_f32_16x16x32_bf16 v[44:47], v[232:235], v[128:131], v[44:47]
	ds_read_b64_tr_b16 v[232:233], v174 offset:37088
	ds_read_b64_tr_b16 v[234:235], v174 offset:41696
	s_waitcnt lgkmcnt(10)
	v_mfma_f32_16x16x32_bf16 v[40:43], v[236:239], v[120:123], v[40:43]
	v_mfma_f32_16x16x32_bf16 v[48:51], v[236:239], v[128:131], v[48:51]
	ds_read_b64_tr_b16 v[236:237], v174 offset:46080
	ds_read_b64_tr_b16 v[238:239], v174 offset:50688
	s_waitcnt lgkmcnt(10)
	v_mfma_f32_16x16x32_bf16 v[52:55], v[240:243], v[120:123], v[52:55]
	v_mfma_f32_16x16x32_bf16 v[60:63], v[240:243], v[128:131], v[60:63]
	ds_read_b64_tr_b16 v[240:241], v174 offset:46112
	ds_read_b64_tr_b16 v[242:243], v174 offset:50720
	s_waitcnt lgkmcnt(10)
	v_mfma_f32_16x16x32_bf16 v[56:59], v[244:247], v[120:123], v[56:59]
	v_mfma_f32_16x16x32_bf16 v[68:71], v[244:247], v[128:131], v[68:71]
	ds_read_b64_tr_b16 v[244:245], v174 offset:46144
	ds_read_b64_tr_b16 v[246:247], v174 offset:50752
	s_waitcnt lgkmcnt(10)
	v_mfma_f32_16x16x32_bf16 v[64:67], v[248:251], v[120:123], v[64:67]
	v_mfma_f32_16x16x32_bf16 v[76:79], v[248:251], v[128:131], v[76:79]
	ds_read_b64_tr_b16 v[248:249], v174 offset:46176
	ds_read_b64_tr_b16 v[250:251], v174 offset:50784
	s_waitcnt lgkmcnt(10)
	v_mfma_f32_16x16x32_bf16 v[72:75], v[228:231], v[120:123], v[72:75]
	v_mfma_f32_16x16x32_bf16 v[80:83], v[228:231], v[128:131], v[80:83]
	ds_read_b64_tr_b16 v[228:229], v174 offset:46208
	ds_read_b64_tr_b16 v[230:231], v174 offset:50816
	s_waitcnt lgkmcnt(10)
	v_mfma_f32_16x16x32_bf16 v[84:87], v[232:235], v[120:123], v[84:87]
	v_mfma_f32_16x16x32_bf16 v[20:23], v[232:235], v[128:131], v[20:23]
	ds_read_b64_tr_b16 v[232:233], v174 offset:46240
	ds_read_b64_tr_b16 v[234:235], v174 offset:50848
	s_waitcnt lgkmcnt(10)
	v_mfma_f32_16x16x32_bf16 v[28:31], v[236:239], v[124:127], v[28:31]
	v_mfma_f32_16x16x32_bf16 v[36:39], v[236:239], v[152:155], v[36:39]
	ds_read_b64_tr_b16 v[236:237], v174 offset:46272
	ds_read_b64_tr_b16 v[238:239], v174 offset:50880
	s_waitcnt lgkmcnt(10)
	v_mfma_f32_16x16x32_bf16 v[32:35], v[240:243], v[124:127], v[32:35]
	v_mfma_f32_16x16x32_bf16 v[44:47], v[240:243], v[152:155], v[44:47]
	ds_read_b64_tr_b16 v[240:241], v174 offset:46304
	ds_read_b64_tr_b16 v[242:243], v174 offset:50912
	s_waitcnt lgkmcnt(10)
	v_mfma_f32_16x16x32_bf16 v[40:43], v[244:247], v[124:127], v[40:43]
	v_mfma_f32_16x16x32_bf16 v[48:51], v[244:247], v[152:155], v[48:51]
	s_waitcnt lgkmcnt(8)
	v_mfma_f32_16x16x32_bf16 v[52:55], v[248:251], v[124:127], v[52:55]
	v_mfma_f32_16x16x32_bf16 v[60:63], v[248:251], v[152:155], v[60:63]
	s_waitcnt lgkmcnt(6)
	v_mfma_f32_16x16x32_bf16 v[56:59], v[228:231], v[124:127], v[56:59]
	v_mfma_f32_16x16x32_bf16 v[68:71], v[228:231], v[152:155], v[68:71]
	s_waitcnt lgkmcnt(4)
	v_mfma_f32_16x16x32_bf16 v[64:67], v[232:235], v[124:127], v[64:67]
	v_mfma_f32_16x16x32_bf16 v[76:79], v[232:235], v[152:155], v[76:79]
	s_waitcnt lgkmcnt(2)
	v_mfma_f32_16x16x32_bf16 v[72:75], v[236:239], v[124:127], v[72:75]
	v_mfma_f32_16x16x32_bf16 v[80:83], v[236:239], v[152:155], v[80:83]
	s_waitcnt lgkmcnt(0)
	v_mfma_f32_16x16x32_bf16 v[84:87], v[240:243], v[124:127], v[84:87]
	v_mfma_f32_16x16x32_bf16 v[20:23], v[240:243], v[152:155], v[20:23]
	s_waitcnt vmcnt(0)
	v_mov_b32_e32 v138, 0xa00
	v_mov_b32_e32 v139, 0x0
	v_mov_b32_e32 v140, 0x9ff
	v_mov_b32_e32 v141, 0x0
	v_mov_b32_e32 v142, 0x200
	v_mov_b32_e32 v143, 0x0
	v_mov_b32_e32 v144, 0x1ff
	v_mov_b32_e32 v145, 0x0
	v_mov_b32_e32 v146, 0xb00
	v_mov_b32_e32 v147, 0x0
	v_mov_b32_e32 v148, 0xaff
	v_mov_b32_e32 v149, 0x0
	v_mov_b32_e32 v194, 0x358637bd
	v_mov_b32_e32 v195, 0x2000
	v_mov_b32_e32 v196, 0x3e38aa3b
	v_mov_b32_e32 v197, 0x41b17218
